# attention: V-fragment reads in QK chain gaps combined with the split bias-init packed adds
# baseline (speedup 1.0000x reference)
.LBB0_572:
	s_add_i32 s9, s9, 3
	s_cmp_lt_u32 s83, 4
	s_cselect_b32 s8, s8, s9
	v_lshl_add_u32 v156, s8, 6, v151
	v_cvt_f32_i32_e32 v66, v156
	s_cmp_lt_i32 s8, s84
	v_fma_f32 v81, v117, v66, -v155
	v_add_f32_e32 v97, v149, v81
	v_pk_add_f32 v[66:67], v[190:191], v[80:81] op_sel:[0,1] op_sel_hi:[1,1]
	v_pk_add_f32 v[68:69], v[134:135], v[80:81] op_sel:[0,1] op_sel_hi:[1,1]
	v_pk_add_f32 v[70:71], v[136:137], v[80:81] op_sel:[0,1] op_sel_hi:[1,1]
	v_pk_add_f32 v[72:73], v[138:139], v[80:81] op_sel:[0,1] op_sel_hi:[1,1]
	v_pk_add_f32 v[74:75], v[140:141], v[80:81] op_sel:[0,1] op_sel_hi:[1,1]
	v_pk_add_f32 v[76:77], v[142:143], v[80:81] op_sel:[0,1] op_sel_hi:[1,1]
	v_pk_add_f32 v[78:79], v[144:145], v[80:81] op_sel:[0,1] op_sel_hi:[1,1]
	v_pk_add_f32 v[80:81], v[216:217], v[80:81] op_sel:[0,1] op_sel_hi:[1,1]
	s_waitcnt lgkmcnt(4)
	s_nop 1
	v_mfma_f32_32x32x16_bf16 v[66:81], v[192:195], v[98:101], v[66:81]
	v_pk_add_f32 v[82:83], v[190:191], v[96:97] op_sel:[0,1] op_sel_hi:[1,1]
	v_pk_add_f32 v[84:85], v[134:135], v[96:97] op_sel:[0,1] op_sel_hi:[1,1]
	v_lshl_add_u32 v188, s81, 14, v152
	ds_read_b64_tr_b16 v[172:173], v188 offset:0
	ds_read_b64_tr_b16 v[174:175], v188 offset:512
	ds_read_b64_tr_b16 v[176:177], v188 offset:4096
	ds_read_b64_tr_b16 v[178:179], v188 offset:4608
	v_mfma_f32_32x32x16_bf16 v[66:81], v[200:203], v[102:105], v[66:81]
	v_pk_add_f32 v[86:87], v[136:137], v[96:97] op_sel:[0,1] op_sel_hi:[1,1]
	v_pk_add_f32 v[88:89], v[138:139], v[96:97] op_sel:[0,1] op_sel_hi:[1,1]
	ds_read_b64_tr_b16 v[180:181], v188 offset:8192
	ds_read_b64_tr_b16 v[182:183], v188 offset:8704
	ds_read_b64_tr_b16 v[184:185], v188 offset:12288
	ds_read_b64_tr_b16 v[186:187], v188 offset:12800
	v_mfma_f32_32x32x16_bf16 v[66:81], v[208:211], v[106:109], v[66:81]
	v_pk_add_f32 v[90:91], v[140:141], v[96:97] op_sel:[0,1] op_sel_hi:[1,1]
	v_pk_add_f32 v[92:93], v[142:143], v[96:97] op_sel:[0,1] op_sel_hi:[1,1]
	v_mfma_f32_32x32x16_bf16 v[66:81], v[220:223], v[110:113], v[66:81]
	v_pk_add_f32 v[94:95], v[144:145], v[96:97] op_sel:[0,1] op_sel_hi:[1,1]
	v_pk_add_f32 v[96:97], v[216:217], v[96:97] op_sel:[0,1] op_sel_hi:[1,1]
	s_waitcnt lgkmcnt(8)
	s_nop 1
	v_mfma_f32_32x32x16_bf16 v[82:97], v[196:199], v[98:101], v[82:97]
	v_mfma_f32_32x32x16_bf16 v[82:97], v[204:207], v[102:105], v[82:97]
	ds_read_b64_tr_b16 v[192:193], v188 offset:1024
	ds_read_b64_tr_b16 v[194:195], v188 offset:1536
	ds_read_b64_tr_b16 v[196:197], v188 offset:5120
	ds_read_b64_tr_b16 v[198:199], v188 offset:5632
	v_mfma_f32_32x32x16_bf16 v[82:97], v[212:215], v[106:109], v[82:97]
	ds_read_b64_tr_b16 v[200:201], v188 offset:9216
	ds_read_b64_tr_b16 v[202:203], v188 offset:9728
	ds_read_b64_tr_b16 v[204:205], v188 offset:13312
	ds_read_b64_tr_b16 v[206:207], v188 offset:13824
	v_mfma_f32_32x32x16_bf16 v[82:97], v[228:231], v[110:113], v[82:97]
	s_cbranch_scc1 .LBB0_574
	s_movk_i32 s36, 0xffe6
	s_movk_i32 s64, 0xffe5
	s_movk_i32 s34, 0xffe7
	v_cmp_lt_i32_e64 s[62:63], s36, v156
	v_cmp_lt_i32_e64 s[64:65], s64, v156
	s_movk_i32 s30, 0xffe8
	v_cmp_lt_i32_e64 s[60:61], s34, v156
	s_and_b64 s[62:63], s[64:65], s[62:63]
	s_movk_i32 s28, 0xffed
	v_cmp_lt_i32_e64 s[58:59], s30, v156
	s_and_b64 s[60:61], s[62:63], s[60:61]
	s_movk_i32 s26, 0xffee
	v_cmp_lt_i32_e64 s[56:57], s28, v156
	s_and_b64 s[58:59], s[60:61], s[58:59]
	s_movk_i32 s24, 0xffef
	v_cmp_lt_i32_e64 s[54:55], s26, v156
	s_and_b64 s[56:57], s[58:59], s[56:57]
	v_cmp_lt_i32_e64 s[52:53], s24, v156
	s_and_b64 s[54:55], s[56:57], s[54:55]
	v_cmp_lt_i32_e64 s[50:51], -16, v156
	s_and_b64 s[52:53], s[54:55], s[52:53]
	v_cmp_lt_i32_e64 s[48:49], -11, v156
	s_and_b64 s[50:51], s[52:53], s[50:51]
	v_cmp_lt_i32_e64 s[46:47], -10, v156
	s_and_b64 s[48:49], s[50:51], s[48:49]
	v_cmp_lt_i32_e64 s[44:45], -9, v156
	s_and_b64 s[46:47], s[48:49], s[46:47]
	s_movk_i32 s10, 0xffe0
	v_cmp_lt_i32_e64 s[42:43], -8, v156
	s_and_b64 s[44:45], s[46:47], s[44:45]
	v_cmp_gt_i32_e64 s[8:9], 1, v156
	v_cmp_lt_i32_e32 vcc, s10, v156
	v_cmp_gt_i32_e64 s[10:11], 0, v156
	v_cmp_lt_i32_e64 s[40:41], -3, v156
	s_and_b64 s[42:43], s[44:45], s[42:43]
	s_or_b64 s[8:9], s[10:11], s[8:9]
	v_cmp_lt_i32_e64 s[38:39], -2, v156
	s_and_b64 s[40:41], s[42:43], s[40:41]
	v_cndmask_b32_e64 v157, v127, v67, s[10:11]
	v_cndmask_b32_e64 v158, v127, v66, s[8:9]
	s_and_b64 s[38:39], s[40:41], s[38:39]
	s_movk_i32 s36, 0xffc6
	v_cndmask_b32_e64 v66, v66, v158, s[38:39]
	v_cndmask_b32_e64 v68, v68, v127, s[38:39]
	v_cndmask_b32_e64 v67, v67, v157, s[38:39]
	s_movk_i32 s38, 0xffc5
	s_movk_i32 s34, 0xffc7
	v_cmp_lt_i32_e64 s[36:37], s36, v156
	v_cmp_lt_i32_e64 s[38:39], s38, v156
	s_movk_i32 s30, 0xffc8
	v_cmp_lt_i32_e64 s[34:35], s34, v156
	s_and_b64 s[36:37], s[38:39], s[36:37]
	s_movk_i32 s28, 0xffcd
	v_cmp_lt_i32_e64 s[30:31], s30, v156
	s_and_b64 s[34:35], s[36:37], s[34:35]
	s_movk_i32 s26, 0xffce
	v_cmp_lt_i32_e64 s[28:29], s28, v156
	s_and_b64 s[30:31], s[34:35], s[30:31]
	s_movk_i32 s24, 0xffcf
	v_cmp_lt_i32_e64 s[26:27], s26, v156
	s_and_b64 s[28:29], s[30:31], s[28:29]
	s_movk_i32 s22, 0xffd0
	v_cmp_lt_i32_e64 s[24:25], s24, v156
	s_and_b64 s[26:27], s[28:29], s[26:27]
	s_movk_i32 s20, 0xffd5
	v_cmp_lt_i32_e64 s[22:23], s22, v156
	s_and_b64 s[24:25], s[26:27], s[24:25]
	s_movk_i32 s18, 0xffd6
	v_cmp_lt_i32_e64 s[20:21], s20, v156
	s_and_b64 s[22:23], s[24:25], s[22:23]
	s_movk_i32 s16, 0xffd7
	v_cmp_lt_i32_e64 s[18:19], s18, v156
	s_and_b64 s[20:21], s[22:23], s[20:21]
	s_movk_i32 s14, 0xffd8
	v_cmp_lt_i32_e64 s[16:17], s16, v156
	s_and_b64 s[18:19], s[20:21], s[18:19]
	s_movk_i32 s12, 0xffdd
	v_cmp_lt_i32_e64 s[14:15], s14, v156
	s_and_b64 s[16:17], s[18:19], s[16:17]
	s_movk_i32 s10, 0xffde
	v_cmp_lt_i32_e64 s[12:13], s12, v156
	s_and_b64 s[14:15], s[16:17], s[14:15]
	s_movk_i32 s8, 0xffdf
	v_cmp_lt_i32_e64 s[10:11], s10, v156
	s_and_b64 s[12:13], s[14:15], s[12:13]
	v_cmp_lt_i32_e64 s[8:9], s8, v156
	s_and_b64 s[10:11], s[12:13], s[10:11]
	s_and_b64 s[8:9], s[10:11], s[8:9]
	s_and_b64 vcc, s[8:9], vcc
	v_cndmask_b32_e64 v81, v81, v127, s[64:65]
	v_cndmask_b32_e64 v80, v80, v127, s[62:63]
	v_cndmask_b32_e64 v79, v79, v127, s[60:61]
	v_cndmask_b32_e64 v78, v78, v127, s[58:59]
	v_cndmask_b32_e64 v77, v77, v127, s[56:57]
	v_cndmask_b32_e64 v76, v76, v127, s[54:55]
	v_cndmask_b32_e64 v75, v75, v127, s[52:53]
	v_cndmask_b32_e64 v74, v74, v127, s[50:51]
	v_cndmask_b32_e64 v73, v73, v127, s[48:49]
	v_cndmask_b32_e64 v72, v72, v127, s[46:47]
	v_cndmask_b32_e64 v71, v71, v127, s[44:45]
	v_cndmask_b32_e64 v70, v70, v127, s[42:43]
	v_cndmask_b32_e64 v69, v69, v127, s[40:41]
	v_cndmask_b32_e64 v97, v97, v127, s[38:39]
	v_cndmask_b32_e64 v96, v96, v127, s[36:37]
	v_cndmask_b32_e64 v95, v95, v127, s[34:35]
	v_cndmask_b32_e64 v94, v94, v127, s[30:31]
	v_cndmask_b32_e64 v93, v93, v127, s[28:29]
	v_cndmask_b32_e64 v92, v92, v127, s[26:27]
	v_cndmask_b32_e64 v91, v91, v127, s[24:25]
	v_cndmask_b32_e64 v90, v90, v127, s[22:23]
	v_cndmask_b32_e64 v89, v89, v127, s[20:21]
	v_cndmask_b32_e64 v88, v88, v127, s[18:19]
	v_cndmask_b32_e64 v87, v87, v127, s[16:17]
	v_cndmask_b32_e64 v86, v86, v127, s[14:15]
	v_cndmask_b32_e64 v85, v85, v127, s[12:13]
	v_cndmask_b32_e64 v84, v84, v127, s[10:11]
	v_cndmask_b32_e64 v83, v83, v127, s[8:9]
	v_cndmask_b32_e32 v82, v82, v127, vcc
